# v_c3 + nt on the 16 adaLN-matvec weight loads in P0 (read-once stream, like the conversion loads)
# speedup vs baseline: 1.0076x; 1.0076x over previous
; #define LAS __attribute__((address_space(3)))
; __device__ __forceinline__ void p0a_phase(LAS unsigned char* lds, KArgs A, int G, int wave_s) {
;     ...
; #pragma unroll 4
;             for (int k = kbeg; k < kbeg + 256; k += 4) {
;                 const f32x4 w0 = *(const f32x4*)(Wl + (size_t)(k + 0) * 12288), w1 = *(const f32x4*)(Wl + (size_t)(k + 1) * 12288);
;                 const f32x4 w2 = *(const f32x4*)(Wl + (size_t)(k + 2) * 12288), w3 = *(const f32x4*)(Wl + (size_t)(k + 3) * 12288);
; #pragma unroll
;                 for (int b = 0; b < 4; ++b) { const f32x4 cv = *(const LAS f32x4*)(cact + b * 2048 + k); acc[b] += cv.x * w0 + cv.y * w1 + cv.z * w2 + cv.w * w3; }
.LBB0_26:
	v_add_co_u32_e64 v22, s[4:5], s25, v20
	v_mov_b32_e32 v16, s15
	s_nop 0
	v_addc_co_u32_e64 v23, s[4:5], -1, v21, s[4:5]
	v_add_co_u32_e64 v24, s[4:5], s24, v20
	s_add_i32 s44, s44, 16
	s_nop 0
	v_addc_co_u32_e64 v25, s[4:5], -1, v21, s[4:5]
	v_add_co_u32_e64 v26, s[4:5], s26, v20
	s_add_i32 s15, s15, 64
	s_nop 0
	v_addc_co_u32_e64 v27, s[4:5], -1, v21, s[4:5]
	v_add_co_u32_e64 v28, s[4:5], s27, v20
	s_cmp_lt_i32 s44, s3
	s_nop 0
	v_addc_co_u32_e64 v29, s[4:5], -1, v21, s[4:5]
	v_add_co_u32_e64 v30, s[4:5], s30, v20
	s_nop 1
	v_addc_co_u32_e64 v31, s[4:5], -1, v21, s[4:5]
	v_add_co_u32_e64 v32, s[4:5], s28, v20
	s_nop 1
	v_addc_co_u32_e64 v33, s[4:5], -1, v21, s[4:5]
	v_add_co_u32_e64 v34, s[4:5], s31, v20
	s_nop 1
	v_addc_co_u32_e64 v35, s[4:5], -1, v21, s[4:5]
	v_add_co_u32_e64 v36, s[4:5], s34, v20
	s_nop 1
	v_addc_co_u32_e64 v37, s[4:5], -1, v21, s[4:5]
	v_add_co_u32_e64 v38, s[4:5], s36, v20
	s_nop 1
	v_addc_co_u32_e64 v39, s[4:5], -1, v21, s[4:5]
	v_add_co_u32_e64 v102, s[4:5], s35, v20
	s_nop 1
	v_addc_co_u32_e64 v103, s[4:5], -1, v21, s[4:5]
	v_add_co_u32_e64 v142, s[4:5], s37, v20
	s_nop 1
	v_addc_co_u32_e64 v143, s[4:5], -1, v21, s[4:5]
	v_add_co_u32_e64 v146, s[4:5], s39, v20
	s_nop 1
	v_addc_co_u32_e64 v147, s[4:5], -1, v21, s[4:5]
	v_add_co_u32_e64 v56, s[4:5], s41, v20
	s_nop 1
	v_addc_co_u32_e64 v57, s[4:5], -1, v21, s[4:5]
	v_add_co_u32_e64 v130, s[4:5], s40, v20
	global_load_dwordx4 v[44:47], v[22:23], off nt
	global_load_dwordx4 v[48:51], v[30:31], off nt
	global_load_dwordx4 v[52:55], v[38:39], off nt
	s_nop 0
	global_load_dwordx4 v[56:59], v[56:57], off nt
	s_nop 0
	global_load_dwordx4 v[22:25], v[24:25], off nt
	v_addc_co_u32_e64 v131, s[4:5], -1, v21, s[4:5]
	ds_read_b128 v[60:63], v16
	ds_read_b128 v[66:69], v16 offset:16
	ds_read_b128 v[70:73], v16 offset:8192
	ds_read_b128 v[74:77], v16 offset:8208
	global_load_dwordx4 v[30:33], v[32:33], off nt
	ds_read_b128 v[78:81], v16 offset:16384
	ds_read_b128 v[82:85], v16 offset:16400
	ds_read_b128 v[86:89], v16 offset:24576
	ds_read_b128 v[90:93], v16 offset:24592
	global_load_dwordx4 v[94:97], v[26:27], off nt
	s_nop 0
	global_load_dwordx4 v[26:29], v[28:29], off nt
	s_nop 0
	global_load_dwordx4 v[98:101], v[34:35], off nt
	s_nop 0
	global_load_dwordx4 v[34:37], v[36:37], off nt
	s_nop 0
	global_load_dwordx4 v[102:105], v[102:103], off nt
	ds_read_b128 v[106:109], v16 offset:32
	ds_read_b128 v[110:113], v16 offset:48
	ds_read_b128 v[114:117], v16 offset:8224
	ds_read_b128 v[118:121], v16 offset:8240
	ds_read_b128 v[122:125], v16 offset:16416
	ds_read_b128 v[126:129], v16 offset:16432
	global_load_dwordx4 v[130:133], v[130:131], off nt
	v_add_co_u32_e64 v150, s[4:5], s42, v20
	ds_read_b128 v[134:137], v16 offset:24608
	ds_read_b128 v[138:141], v16 offset:24624
	v_addc_co_u32_e64 v151, s[4:5], -1, v21, s[4:5]
	global_load_dwordx4 v[142:145], v[142:143], off nt
	s_nop 0
	global_load_dwordx4 v[146:149], v[146:147], off nt
	s_nop 0
	global_load_dwordx4 v[150:153], v[150:151], off nt
	s_nop 0
	global_load_dwordx4 v[154:157], v[20:21], off nt
	s_waitcnt lgkmcnt(14)
	v_mov_b32_e32 v16, v63
	s_waitcnt lgkmcnt(13)
	v_mov_b32_e32 v38, v73
	s_waitcnt lgkmcnt(11)
	v_mov_b32_e32 v158, v81
	s_waitcnt lgkmcnt(9)
	v_mov_b32_e32 v160, v89
	v_mov_b32_e32 v162, v69
	v_mov_b32_e32 v164, v77
	v_mov_b32_e32 v166, v85
	s_waitcnt lgkmcnt(8)
	v_mov_b32_e32 v168, v93
	s_waitcnt lgkmcnt(7)
	v_mov_b32_e32 v170, v109
	s_waitcnt lgkmcnt(5)
	v_mov_b32_e32 v172, v117
	s_waitcnt lgkmcnt(3)
	v_mov_b32_e32 v174, v125
	s_waitcnt lgkmcnt(1)
	v_mov_b32_e32 v176, v137
	v_mov_b32_e32 v178, v113
	v_mov_b32_e32 v180, v121
	v_mov_b32_e32 v182, v129
	s_waitcnt lgkmcnt(0)
	v_mov_b32_e32 v184, v141
	v_lshl_add_u64 v[20:21], v[20:21], 0, s[12:13]
	s_waitcnt vmcnt(15)
	v_pk_mul_f32 v[186:187], v[46:47], v[60:61] op_sel:[0,1]
	v_pk_mul_f32 v[188:189], v[44:45], v[60:61] op_sel:[0,1]
	v_pk_mul_f32 v[190:191], v[46:47], v[70:71] op_sel:[0,1]
	v_pk_mul_f32 v[192:193], v[44:45], v[70:71] op_sel:[0,1]
	v_pk_mul_f32 v[194:195], v[46:47], v[78:79] op_sel:[0,1]
	v_pk_mul_f32 v[196:197], v[44:45], v[78:79] op_sel:[0,1]
	v_pk_mul_f32 v[46:47], v[46:47], v[86:87] op_sel:[0,1]
	v_pk_mul_f32 v[44:45], v[44:45], v[86:87] op_sel:[0,1]
	s_waitcnt vmcnt(14)
	v_pk_mul_f32 v[198:199], v[50:51], v[66:67] op_sel:[0,1]
	v_pk_mul_f32 v[200:201], v[48:49], v[66:67] op_sel:[0,1]
	v_pk_mul_f32 v[202:203], v[50:51], v[74:75] op_sel:[0,1]
	v_pk_mul_f32 v[204:205], v[48:49], v[74:75] op_sel:[0,1]
	v_pk_mul_f32 v[206:207], v[50:51], v[82:83] op_sel:[0,1]
	v_pk_mul_f32 v[208:209], v[48:49], v[82:83] op_sel:[0,1]
	v_pk_mul_f32 v[50:51], v[50:51], v[90:91] op_sel:[0,1]
	v_pk_mul_f32 v[48:49], v[48:49], v[90:91] op_sel:[0,1]
	s_waitcnt vmcnt(13)
	v_pk_mul_f32 v[210:211], v[54:55], v[106:107] op_sel:[0,1]
	v_pk_mul_f32 v[212:213], v[52:53], v[106:107] op_sel:[0,1]
	v_pk_mul_f32 v[214:215], v[54:55], v[114:115] op_sel:[0,1]
	v_pk_mul_f32 v[216:217], v[52:53], v[114:115] op_sel:[0,1]
	v_pk_mul_f32 v[218:219], v[54:55], v[122:123] op_sel:[0,1]
	v_pk_mul_f32 v[220:221], v[52:53], v[122:123] op_sel:[0,1]
	v_pk_mul_f32 v[54:55], v[54:55], v[134:135] op_sel:[0,1]
	v_pk_mul_f32 v[52:53], v[52:53], v[134:135] op_sel:[0,1]
	s_waitcnt vmcnt(12)
	v_pk_mul_f32 v[222:223], v[58:59], v[110:111] op_sel:[0,1]
	v_pk_mul_f32 v[224:225], v[56:57], v[110:111] op_sel:[0,1]
	v_pk_mul_f32 v[226:227], v[58:59], v[118:119] op_sel:[0,1]
	v_pk_mul_f32 v[228:229], v[56:57], v[118:119] op_sel:[0,1]
	v_pk_mul_f32 v[230:231], v[58:59], v[126:127] op_sel:[0,1]
	v_pk_mul_f32 v[232:233], v[56:57], v[126:127] op_sel:[0,1]
	v_pk_mul_f32 v[56:57], v[56:57], v[138:139] op_sel:[0,1]
	s_waitcnt vmcnt(11)
; #define LAS __attribute__((address_space(3)))
; __device__ __forceinline__ void p0a_phase(LAS unsigned char* lds, KArgs A, int G, int wave_s) {
;     ...
;             for (int k = kbeg; k < kbeg + 256; k += 4) {
;                 const f32x4 w0 = *(const f32x4*)(Wl + (size_t)(k + 0) * 12288), w1 = *(const f32x4*)(Wl + (size_t)(k + 1) * 12288);
;                 const f32x4 w2 = *(const f32x4*)(Wl + (size_t)(k + 2) * 12288), w3 = *(const f32x4*)(Wl + (size_t)(k + 3) * 12288);
; #pragma unroll
;                 for (int b = 0; b < 4; ++b) { const f32x4 cv = *(const LAS f32x4*)(cact + b * 2048 + k); acc[b] += cv.x * w0 + cv.y * w1 + cv.z * w2 + cv.w * w3; }
;             }
	v_pk_fma_f32 v[186:187], v[24:25], v[60:61], v[186:187] op_sel_hi:[1,0,1]
	v_pk_fma_f32 v[60:61], v[22:23], v[60:61], v[188:189] op_sel_hi:[1,0,1]
	v_pk_fma_f32 v[188:189], v[24:25], v[70:71], v[190:191] op_sel_hi:[1,0,1]
	v_pk_fma_f32 v[70:71], v[22:23], v[70:71], v[192:193] op_sel_hi:[1,0,1]
	v_pk_fma_f32 v[190:191], v[24:25], v[78:79], v[194:195] op_sel_hi:[1,0,1]
	v_pk_fma_f32 v[78:79], v[22:23], v[78:79], v[196:197] op_sel_hi:[1,0,1]
	v_pk_fma_f32 v[24:25], v[24:25], v[86:87], v[46:47] op_sel_hi:[1,0,1]
	v_pk_fma_f32 v[22:23], v[22:23], v[86:87], v[44:45] op_sel_hi:[1,0,1]
	s_waitcnt vmcnt(10)
	v_pk_fma_f32 v[44:45], v[32:33], v[66:67], v[198:199] op_sel_hi:[1,0,1]
	v_pk_fma_f32 v[46:47], v[30:31], v[66:67], v[200:201] op_sel_hi:[1,0,1]
	v_pk_fma_f32 v[66:67], v[32:33], v[74:75], v[202:203] op_sel_hi:[1,0,1]
	v_pk_fma_f32 v[74:75], v[30:31], v[74:75], v[204:205] op_sel_hi:[1,0,1]
	v_pk_fma_f32 v[86:87], v[32:33], v[82:83], v[206:207] op_sel_hi:[1,0,1]
	v_pk_fma_f32 v[82:83], v[30:31], v[82:83], v[208:209] op_sel_hi:[1,0,1]
	v_pk_fma_f32 v[32:33], v[32:33], v[90:91], v[50:51] op_sel_hi:[1,0,1]
	v_pk_fma_f32 v[30:31], v[30:31], v[90:91], v[48:49] op_sel_hi:[1,0,1]
	s_waitcnt vmcnt(5)
	v_pk_fma_f32 v[48:49], v[104:105], v[106:107], v[210:211] op_sel_hi:[1,0,1]
	v_pk_fma_f32 v[50:51], v[102:103], v[106:107], v[212:213] op_sel_hi:[1,0,1]
	v_pk_fma_f32 v[90:91], v[104:105], v[114:115], v[214:215] op_sel_hi:[1,0,1]
	v_pk_fma_f32 v[106:107], v[102:103], v[114:115], v[216:217] op_sel_hi:[1,0,1]
	v_pk_fma_f32 v[114:115], v[104:105], v[122:123], v[218:219] op_sel_hi:[1,0,1]
	v_pk_fma_f32 v[122:123], v[102:103], v[122:123], v[220:221] op_sel_hi:[1,0,1]
	v_pk_fma_f32 v[54:55], v[104:105], v[134:135], v[54:55] op_sel_hi:[1,0,1]
	v_pk_fma_f32 v[52:53], v[102:103], v[134:135], v[52:53] op_sel_hi:[1,0,1]
	s_waitcnt vmcnt(4)
	v_pk_fma_f32 v[102:103], v[132:133], v[110:111], v[222:223] op_sel_hi:[1,0,1]
	v_pk_fma_f32 v[104:105], v[130:131], v[110:111], v[224:225] op_sel_hi:[1,0,1]
	v_pk_fma_f32 v[110:111], v[132:133], v[118:119], v[226:227] op_sel_hi:[1,0,1]
	v_pk_fma_f32 v[118:119], v[130:131], v[118:119], v[228:229] op_sel_hi:[1,0,1]
	v_pk_fma_f32 v[134:135], v[132:133], v[126:127], v[230:231] op_sel_hi:[1,0,1]
	v_pk_fma_f32 v[126:127], v[130:131], v[126:127], v[232:233] op_sel_hi:[1,0,1]
	v_pk_fma_f32 v[56:57], v[130:131], v[138:139], v[56:57] op_sel_hi:[1,0,1]
	v_pk_fma_f32 v[130:131], v[96:97], v[62:63], v[186:187] op_sel_hi:[1,0,1]
	v_pk_fma_f32 v[60:61], v[94:95], v[62:63], v[60:61] op_sel_hi:[1,0,1]
	v_pk_fma_f32 v[62:63], v[96:97], v[72:73], v[188:189] op_sel_hi:[1,0,1]
	v_pk_fma_f32 v[70:71], v[94:95], v[72:73], v[70:71] op_sel_hi:[1,0,1]
	v_pk_fma_f32 v[72:73], v[96:97], v[80:81], v[190:191] op_sel_hi:[1,0,1]
	v_pk_fma_f32 v[78:79], v[94:95], v[80:81], v[78:79] op_sel_hi:[1,0,1]
	v_pk_fma_f32 v[24:25], v[96:97], v[88:89], v[24:25] op_sel_hi:[1,0,1]
	v_pk_fma_f32 v[22:23], v[94:95], v[88:89], v[22:23] op_sel_hi:[1,0,1]
	v_pk_mul_f32 v[58:59], v[58:59], v[138:139] op_sel:[0,1]
	v_pk_fma_f32 v[44:45], v[100:101], v[68:69], v[44:45] op_sel_hi:[1,0,1]
	v_pk_fma_f32 v[46:47], v[98:99], v[68:69], v[46:47] op_sel_hi:[1,0,1]
	v_pk_fma_f32 v[66:67], v[100:101], v[76:77], v[66:67] op_sel_hi:[1,0,1]
	v_pk_fma_f32 v[68:69], v[98:99], v[76:77], v[74:75] op_sel_hi:[1,0,1]
	v_pk_fma_f32 v[74:75], v[100:101], v[84:85], v[86:87] op_sel_hi:[1,0,1]
	v_pk_fma_f32 v[76:77], v[98:99], v[84:85], v[82:83] op_sel_hi:[1,0,1]
	v_pk_fma_f32 v[32:33], v[100:101], v[92:93], v[32:33] op_sel_hi:[1,0,1]
	v_pk_fma_f32 v[30:31], v[98:99], v[92:93], v[30:31] op_sel_hi:[1,0,1]
	v_pk_fma_f32 v[100:101], v[28:29], v[16:17], v[130:131] op_sel_hi:[1,0,1]
	v_pk_fma_f32 v[60:61], v[26:27], v[16:17], v[60:61] op_sel_hi:[1,0,1]
	v_pk_fma_f32 v[62:63], v[28:29], v[38:39], v[62:63] op_sel_hi:[1,0,1]
	v_pk_fma_f32 v[38:39], v[26:27], v[38:39], v[70:71] op_sel_hi:[1,0,1]
	v_pk_fma_f32 v[70:71], v[28:29], v[158:159], v[72:73] op_sel_hi:[1,0,1]
	v_pk_fma_f32 v[72:73], v[26:27], v[158:159], v[78:79] op_sel_hi:[1,0,1]
	v_pk_fma_f32 v[24:25], v[28:29], v[160:161], v[24:25] op_sel_hi:[1,0,1]
	v_pk_fma_f32 v[22:23], v[26:27], v[160:161], v[22:23] op_sel_hi:[1,0,1]
	v_pk_fma_f32 v[58:59], v[132:133], v[138:139], v[58:59] op_sel_hi:[1,0,1]
	s_waitcnt vmcnt(3)
	v_pk_fma_f32 v[48:49], v[144:145], v[108:109], v[48:49] op_sel_hi:[1,0,1]
	v_pk_fma_f32 v[50:51], v[142:143], v[108:109], v[50:51] op_sel_hi:[1,0,1]
	v_pk_fma_f32 v[80:81], v[144:145], v[116:117], v[90:91] op_sel_hi:[1,0,1]
	v_pk_fma_f32 v[82:83], v[142:143], v[116:117], v[106:107] op_sel_hi:[1,0,1]
	v_pk_fma_f32 v[84:85], v[144:145], v[124:125], v[114:115] op_sel_hi:[1,0,1]
	v_pk_fma_f32 v[86:87], v[142:143], v[124:125], v[122:123] op_sel_hi:[1,0,1]
	v_pk_fma_f32 v[54:55], v[144:145], v[136:137], v[54:55] op_sel_hi:[1,0,1]
	v_pk_fma_f32 v[52:53], v[142:143], v[136:137], v[52:53] op_sel_hi:[1,0,1]
	v_pk_fma_f32 v[26:27], v[36:37], v[162:163], v[44:45] op_sel_hi:[1,0,1]
	v_pk_fma_f32 v[28:29], v[34:35], v[162:163], v[46:47] op_sel_hi:[1,0,1]
	v_pk_fma_f32 v[44:45], v[36:37], v[164:165], v[66:67] op_sel_hi:[1,0,1]
	v_pk_fma_f32 v[46:47], v[34:35], v[164:165], v[68:69] op_sel_hi:[1,0,1]
	v_pk_fma_f32 v[66:67], v[36:37], v[166:167], v[74:75] op_sel_hi:[1,0,1]
	v_pk_fma_f32 v[68:69], v[34:35], v[166:167], v[76:77] op_sel_hi:[1,0,1]
	v_pk_fma_f32 v[32:33], v[36:37], v[168:169], v[32:33] op_sel_hi:[1,0,1]
	v_pk_fma_f32 v[30:31], v[34:35], v[168:169], v[30:31] op_sel_hi:[1,0,1]
	v_pk_add_f32 v[14:15], v[14:15], v[100:101]
	v_pk_add_f32 v[12:13], v[12:13], v[60:61]
	v_pk_add_f32 v[10:11], v[10:11], v[62:63]
	v_pk_add_f32 v[8:9], v[8:9], v[38:39]
	v_pk_add_f32 v[6:7], v[6:7], v[70:71]
	v_pk_add_f32 v[4:5], v[4:5], v[72:73]
	v_pk_add_f32 v[2:3], v[2:3], v[24:25]
	v_pk_add_f32 v[0:1], v[0:1], v[22:23]
	s_waitcnt vmcnt(1)
; #define LAS __attribute__((address_space(3)))
; __device__ __forceinline__ void p0a_phase(LAS unsigned char* lds, KArgs A, int G, int wave_s) {
;     ...
;                 for (int b = 0; b < 4; ++b) { const f32x4 cv = *(const LAS f32x4*)(cact + b * 2048 + k); acc[b] += cv.x * w0 + cv.y * w1 + cv.z * w2 + cv.w * w3; }
;             }
; #pragma unroll
;             for (int b = 0; b < 4; ++b) *(LAS f32x4*)(red + (wave * 4 + b) * 256 + 4 * lane) = acc[b];
;             __syncthreads();
;             { const int b = tid >> 7, c0 = 2 * (tid & 127); float s0 = 0.f, s1 = 0.f;
; #pragma unroll
;               for (int w = 0; w < 8; ++w) { s0 += red[(w * 4 + b) * 256 + c0]; s1 += red[(w * 4 + b) * 256 + c0 + 1]; }
;               const int col = cg * 256 + c0;
;               MOD[(size_t)(layer * 4 + b) * 12288 + col] = s0 + ada_b[layer * 12288 + col];
;               MOD[(size_t)(layer * 4 + b) * 12288 + col + 1] = s1 + ada_b[layer * 12288 + col + 1]; }
;             asm volatile("s_waitcnt vmcnt(0)" ::: "memory");
;             __syncthreads();
;             if (layer == 0 && cg < 16 && tid == 0) {
;                 __builtin_amdgcn_fence(__ATOMIC_RELEASE, "agent"); asm volatile("s_waitcnt vmcnt(0)" ::: "memory");
;                 __hip_atomic_fetch_add((unsigned*)(ws + WS_CTL) + CW_MODRDY, 1u, __ATOMIC_RELAXED, __HIP_MEMORY_SCOPE_AGENT); }
	v_pk_fma_f32 v[88:89], v[152:153], v[112:113], v[102:103] op_sel_hi:[1,0,1]
	v_pk_fma_f32 v[90:91], v[150:151], v[112:113], v[104:105] op_sel_hi:[1,0,1]
	v_pk_fma_f32 v[92:93], v[152:153], v[120:121], v[110:111] op_sel_hi:[1,0,1]
	v_pk_fma_f32 v[94:95], v[150:151], v[120:121], v[118:119] op_sel_hi:[1,0,1]
	v_pk_fma_f32 v[96:97], v[152:153], v[128:129], v[134:135] op_sel_hi:[1,0,1]
	v_pk_fma_f32 v[98:99], v[150:151], v[128:129], v[126:127] op_sel_hi:[1,0,1]
	v_pk_fma_f32 v[58:59], v[152:153], v[140:141], v[58:59] op_sel_hi:[1,0,1]
	v_pk_fma_f32 v[56:57], v[150:151], v[140:141], v[56:57] op_sel_hi:[1,0,1]
	v_pk_fma_f32 v[34:35], v[148:149], v[170:171], v[48:49] op_sel_hi:[1,0,1]
	v_pk_fma_f32 v[36:37], v[146:147], v[170:171], v[50:51] op_sel_hi:[1,0,1]
	v_pk_fma_f32 v[48:49], v[148:149], v[172:173], v[80:81] op_sel_hi:[1,0,1]
	v_pk_fma_f32 v[50:51], v[146:147], v[172:173], v[82:83] op_sel_hi:[1,0,1]
	v_pk_fma_f32 v[74:75], v[148:149], v[174:175], v[84:85] op_sel_hi:[1,0,1]
	v_pk_fma_f32 v[76:77], v[146:147], v[174:175], v[86:87] op_sel_hi:[1,0,1]
	v_pk_fma_f32 v[54:55], v[148:149], v[176:177], v[54:55] op_sel_hi:[1,0,1]
	v_pk_fma_f32 v[52:53], v[146:147], v[176:177], v[52:53] op_sel_hi:[1,0,1]
	v_pk_add_f32 v[14:15], v[14:15], v[26:27]
	v_pk_add_f32 v[12:13], v[12:13], v[28:29]
	v_pk_add_f32 v[10:11], v[10:11], v[44:45]
	v_pk_add_f32 v[8:9], v[8:9], v[46:47]
	v_pk_add_f32 v[6:7], v[6:7], v[66:67]
	v_pk_add_f32 v[4:5], v[4:5], v[68:69]
	v_pk_add_f32 v[2:3], v[2:3], v[32:33]
	v_pk_add_f32 v[0:1], v[0:1], v[30:31]
	s_waitcnt vmcnt(0)
	v_pk_fma_f32 v[78:79], v[156:157], v[178:179], v[88:89] op_sel_hi:[1,0,1]
	v_pk_fma_f32 v[80:81], v[154:155], v[178:179], v[90:91] op_sel_hi:[1,0,1]
	v_pk_fma_f32 v[82:83], v[156:157], v[180:181], v[92:93] op_sel_hi:[1,0,1]
	v_pk_fma_f32 v[84:85], v[154:155], v[180:181], v[94:95] op_sel_hi:[1,0,1]
	v_pk_fma_f32 v[86:87], v[156:157], v[182:183], v[96:97] op_sel_hi:[1,0,1]
	v_pk_fma_f32 v[88:89], v[154:155], v[182:183], v[98:99] op_sel_hi:[1,0,1]
	v_pk_fma_f32 v[58:59], v[156:157], v[184:185], v[58:59] op_sel_hi:[1,0,1]
	v_pk_fma_f32 v[56:57], v[154:155], v[184:185], v[56:57] op_sel_hi:[1,0,1]
	v_pk_add_f32 v[14:15], v[14:15], v[34:35]
	v_pk_add_f32 v[12:13], v[12:13], v[36:37]
	v_pk_add_f32 v[10:11], v[10:11], v[48:49]
	v_pk_add_f32 v[8:9], v[8:9], v[50:51]
	v_pk_add_f32 v[6:7], v[6:7], v[74:75]
	v_pk_add_f32 v[4:5], v[4:5], v[76:77]
	v_pk_add_f32 v[2:3], v[2:3], v[54:55]
	v_pk_add_f32 v[0:1], v[0:1], v[52:53]
	v_pk_add_f32 v[14:15], v[14:15], v[78:79]
	v_pk_add_f32 v[12:13], v[12:13], v[80:81]
	v_pk_add_f32 v[10:11], v[10:11], v[82:83]
	v_pk_add_f32 v[8:9], v[8:9], v[84:85]
	v_pk_add_f32 v[6:7], v[6:7], v[86:87]
	v_pk_add_f32 v[4:5], v[4:5], v[88:89]
	v_pk_add_f32 v[2:3], v[2:3], v[58:59]
	v_pk_add_f32 v[0:1], v[0:1], v[56:57]
	s_cbranch_scc1 .LBB0_26
	v_or_b32_e32 v20, s14, v42
	s_mul_i32 s4, s19, 0x3000
	ds_write_b128 v40, v[12:15] offset:32768
	ds_write_b128 v40, v[8:11] offset:33792
	ds_write_b128 v40, v[4:7] offset:34816
	ds_write_b128 v40, v[0:3] offset:35840
	v_add_u32_e32 v0, s4, v20
	v_ashrrev_i32_e32 v1, 31, v0
	v_lshl_add_u64 v[22:23], v[0:1], 2, s[0:1]
	s_waitcnt lgkmcnt(0)
	s_barrier
	global_load_dword v16, v[22:23], off
	ds_read2st64_b64 v[0:3], v43 offset0:64 offset1:72
	ds_read2st64_b64 v[4:7], v43 offset0:80 offset1:88
	ds_read2st64_b64 v[8:11], v43 offset0:96 offset1:104
	ds_read2st64_b64 v[12:15], v43 offset0:112 offset1:120
	v_lshl_add_u32 v26, s19, 2, v41
	s_waitcnt lgkmcnt(3)
	v_add_f32_e32 v0, 0, v0
	v_add_f32_e32 v0, v0, v2
	s_waitcnt lgkmcnt(2)
	v_add_f32_e32 v0, v0, v4
	v_add_f32_e32 v0, v0, v6
	s_waitcnt lgkmcnt(1)
	v_add_f32_e32 v0, v0, v8
	v_add_f32_e32 v0, v0, v10
	v_mov_b64_e32 v[24:25], s[6:7]
	s_waitcnt lgkmcnt(0)
	v_add_f32_e32 v0, v0, v12
	v_ashrrev_i32_e32 v21, 31, v20
	v_mad_i64_i32 v[24:25], s[4:5], v26, s22, v[24:25]
	v_add_f32_e32 v0, v0, v14
	v_lshl_add_u64 v[20:21], v[20:21], 2, v[24:25]
	v_add_f32_e32 v1, 0, v1
	v_add_f32_e32 v1, v1, v3
	v_add_f32_e32 v1, v1, v5
	v_add_f32_e32 v1, v1, v7
	v_add_f32_e32 v1, v1, v9
	v_add_f32_e32 v1, v1, v11
	v_add_f32_e32 v1, v1, v13
	s_add_i32 s4, s43, 47
	v_add_f32_e32 v1, v1, v15
	s_cmpk_lt_u32 s4, 0x5f
	s_cselect_b64 s[4:5], -1, 0
	s_cmp_lt_i32 s18, 16
	s_cselect_b64 s[14:15], -1, 0
	s_and_b64 s[4:5], s[4:5], s[14:15]
	s_and_b64 s[4:5], vcc, s[4:5]
	s_waitcnt vmcnt(0)
	v_add_f32_e32 v0, v0, v16
	global_store_dword v[20:21], v0, off
	global_load_dword v0, v[22:23], off offset:4
	s_waitcnt vmcnt(0)
	v_add_f32_e32 v0, v1, v0
	global_store_dword v[20:21], v0, off offset:4
	s_waitcnt vmcnt(0)
	s_barrier
	s_and_saveexec_b64 s[14:15], s[4:5]
	s_cbranch_execz .LBB0_24
	s_mov_b64 s[18:19], exec
	v_mbcnt_lo_u32_b32 v0, s18, 0
	buffer_wbl2 sc1
	s_waitcnt vmcnt(0)
	s_waitcnt vmcnt(0)
	v_mbcnt_hi_u32_b32 v0, s19, v0
	v_cmp_eq_u32_e64 s[4:5], 0, v0
	s_and_b64 s[4:5], exec, s[4:5]
	s_mov_b64 exec, s[4:5]
	s_cbranch_execz .LBB0_24
	s_bcnt1_i32_b64 s4, s[18:19]
	v_mov_b32_e32 v0, s4
	global_atomic_add v17, v0, s[8:9]
	s_branch .LBB0_24
